# mixer first grab stagger lengthened: workgroups 256..511 sleep ~20us (6 x s_sleep 127) instead of ~10us
# speedup vs baseline: 1.0012x; 1.0012x over previous
.LBB0_299:
	s_or_b64 exec, exec, s[4:5]
	v_readlane_b32 s4, v254, 57
	v_readlane_b32 s5, v254, 58
	s_lshl_b32 s90, s4, 4
	s_lshl_b64 s[4:5], s[90:91], 2
	s_add_u32 s4, s42, s4
	s_addc_u32 s5, s43, s5
	v_readlane_b32 s6, v254, 29
	s_add_u32 s6, s4, s6
	s_addc_u32 s7, s5, 0
	v_writelane_b32 v254, s6, 61
	s_barrier
	s_nop 0
	v_writelane_b32 v254, s7, 62
	s_nop 0
	v_readlane_b32 s6, v254, 31
	s_add_u32 s6, s4, s6
	s_addc_u32 s7, s5, 0
	v_writelane_b32 v254, s6, 63
	s_nop 1
	v_writelane_b32 v255, s7, 0
	v_readlane_b32 s6, v254, 33
	s_add_u32 s6, s4, s6
	s_addc_u32 s7, s5, 0
	v_writelane_b32 v255, s6, 1
	s_nop 1
	v_writelane_b32 v255, s7, 2
	v_readlane_b32 s6, v254, 35
	s_add_u32 s6, s4, s6
	s_addc_u32 s7, s5, 0
	v_writelane_b32 v255, s6, 3
	s_nop 1
	v_writelane_b32 v255, s7, 4
	v_readlane_b32 s6, v254, 37
	s_add_u32 s6, s4, s6
	s_addc_u32 s7, s5, 0
	v_writelane_b32 v255, s6, 5
	s_nop 1
	v_writelane_b32 v255, s7, 6
	v_readlane_b32 s6, v254, 39
	s_add_u32 s6, s4, s6
	s_addc_u32 s7, s5, 0
	v_writelane_b32 v255, s6, 7
	s_nop 1
	v_writelane_b32 v255, s7, 8
	v_readlane_b32 s6, v254, 41
	s_add_u32 s6, s4, s6
	s_addc_u32 s7, s5, 0
	v_writelane_b32 v255, s6, 9
	s_nop 1
	v_writelane_b32 v255, s7, 10
	v_readlane_b32 s6, v254, 43
	s_add_u32 s4, s4, s6
	s_addc_u32 s5, s5, 0
	v_writelane_b32 v255, s4, 11
	s_nop 1
	v_writelane_b32 v255, s5, 12
	v_readlane_b32 s6, v254, 13
	s_cmpk_lt_u32 s6, 0x100
	s_cbranch_scc1 .Lmx_nodelay
	s_sleep 127
	s_sleep 127
	s_sleep 127
	s_sleep 127
	s_sleep 127
	s_sleep 127
